# LoRA GEMM: cost-balanced static unit mapping + skip the structurally-zero K half of the block-structured LoRA weights (nt=2)
# speedup vs baseline: 1.0073x; 1.0073x over previous
.Llmap0_done:
	s_cmp_ge_u32 s54, 6
	s_cselect_b32 s98, 0x100, 0
.LBB0_639:
	s_andn2_b64 vcc, exec, s[24:25]
	s_cbranch_vccnz .LBB0_880
	v_ashrrev_i32_e32 v3, 31, v0
	v_lshrrev_b32_e32 v3, 26, v3
	v_lshlrev_b32_e32 v2, 4, v0
	v_add_u32_e32 v3, v0, v3
	v_bfe_i32 v0, v0, 27, 1
	v_lshrrev_b32_e32 v0, 22, v0
	v_add_u32_e32 v0, v2, v0
	v_and_b32_e32 v0, 0xfffffc00, v0
	v_sub_u32_e32 v0, v2, v0
	v_lshrrev_b32_e32 v4, 4, v0
	v_bitop3_b32 v0, v4, v0, 32 bitop3:0x6c
	v_ashrrev_i32_e32 v5, 31, v0
	v_ashrrev_i32_e32 v3, 6, v3
	v_lshrrev_b32_e32 v5, 26, v5
	v_lshlrev_b32_e32 v4, 3, v3
	v_add_u32_e32 v5, v0, v5
	v_and_b32_e32 v4, -16, v4
	v_ashrrev_i32_e32 v6, 6, v5
	v_lshlrev_b32_e32 v3, 5, v3
	v_add_u32_e32 v4, v6, v4
	v_and_b32_e32 v14, 32, v3
	v_and_b32_e32 v3, 0xc0, v5
	v_sub_u32_e32 v0, v0, v3
	v_mov_b32_e32 v7, 1
	v_lshlrev_b32_e32 v3, 1, v4
	v_lshrrev_b32_e32 v5, 2, v4
	v_and_b32_e32 v6, 3, v6
	s_mov_b32 s24, 0x7fffffe0
	v_ashrrev_i16_sdwa v0, v7, sext(v0) dst_sel:DWORD dst_unused:UNUSED_PAD src0_sel:DWORD src1_sel:BYTE_0
	v_and_b32_e32 v3, 24, v3
	v_and_b32_e32 v5, 4, v5
	v_and_or_b32 v6, v4, s24, v6
	v_bfe_i32 v15, v0, 0, 16
	v_or3_b32 v3, v6, v5, v3
	v_add_u32_e32 v0, v14, v15
	v_mul_lo_u32 v16, v4, s42
	v_mul_lo_u32 v3, v3, s42
	v_add_u32_e32 v2, 0x2000, v2
	v_add_lshl_u32 v188, v0, v16, 1
	v_add_lshl_u32 v0, v3, v0, 1
	v_ashrrev_i32_e32 v3, 31, v2
	v_lshrrev_b32_e32 v3, 22, v3
	v_add_u32_e32 v3, v2, v3
	v_ashrrev_i32_e32 v3, 10, v3
	v_mul_i32_i24_e32 v4, 0x400, v3
	v_sub_u32_e32 v2, v2, v4
	v_lshrrev_b32_e32 v4, 4, v2
	v_bitop3_b32 v2, v4, v2, 32 bitop3:0x6c
	v_ashrrev_i32_e32 v5, 31, v2
	v_lshrrev_b32_e32 v5, 26, v5
	v_readlane_b32 s13, v254, 40
	v_lshlrev_b32_e32 v4, 3, v3
	v_add_u32_e32 v5, v2, v5
	s_add_u32 s35, s13, 0x2900000
	v_readlane_b32 s13, v254, 39
	v_and_b32_e32 v4, -16, v4
	v_ashrrev_i32_e32 v6, 6, v5
	s_addc_u32 s36, s13, 0
	v_add_u32_e32 v4, v6, v4
	v_and_b32_e32 v6, 3, v6
	s_ashr_i32 s43, s42, 31
	v_and_or_b32 v6, v4, s24, v6
	s_lshl_b64 s[52:53], s[42:43], 9
	s_ashr_i32 s24, s55, 31
	s_mul_i32 s24, s52, s24
	s_mul_hi_u32 s25, s52, s55
	s_ashr_i32 s27, s54, 31
	s_add_i32 s26, s25, s24
	s_lshr_b64 s[24:25], s[42:43], 23
	s_mul_i32 s27, s52, s27
	s_mul_hi_u32 s28, s52, s54
	v_lshlrev_b32_e32 v3, 5, v3
	s_ashr_i32 s45, s44, 6
	s_mul_i32 s25, s24, s55
	s_add_i32 s27, s28, s27
	s_mul_i32 s24, s24, s54
	s_ashr_i32 s13, s44, 8
	v_and_b32_e32 v17, 32, v3
	v_and_b32_e32 v3, 0xc0, v5
	s_lshl_b64 s[50:51], s[42:43], 8
	s_lshl_b32 s37, s45, 10
	s_add_i32 s26, s26, s25
	s_add_i32 s27, s27, s24
	s_mul_i32 s24, s52, s54
	v_sub_u32_e32 v2, v2, v3
	v_lshlrev_b32_e32 v3, 1, v4
	v_lshrrev_b32_e32 v5, 2, v4
	s_add_u32 s46, s35, s24
	v_ashrrev_i16_sdwa v2, v7, sext(v2) dst_sel:DWORD dst_unused:UNUSED_PAD src0_sel:DWORD src1_sel:BYTE_0
	v_and_b32_e32 v3, 24, v3
	v_and_b32_e32 v5, 4, v5
	s_addc_u32 s47, s36, s27
	s_add_u32 s46, s46, s98
	s_addc_u32 s47, s47, 0
	s_add_i32 s70, s37, 0
	v_bfe_i32 v18, v2, 0, 16
	v_or3_b32 v3, v6, v5, v3
	s_add_i32 m0, s70, 0x10000
	v_add_u32_e32 v2, v17, v18
	v_mul_lo_u32 v3, v3, s42
	global_load_lds_dwordx4 v0, s[46:47]
	s_add_i32 m0, s70, 0x12000
	v_add_lshl_u32 v192, v3, v2, 1
	s_add_u32 s56, s46, s50
	global_load_lds_dwordx4 v192, s[46:47]
	s_addc_u32 s57, s47, s51
	s_add_i32 m0, s70, 0x14000
	s_mul_i32 s25, s52, s55
	global_load_lds_dwordx4 v0, s[56:57]
	s_add_i32 m0, s70, 0x16000
	s_add_u32 s24, s14, s25
	s_addc_u32 s25, s15, s26
	s_add_u32 s24, s24, s98
	s_addc_u32 s25, s25, 0
	s_add_i32 s71, s70, 0x2000
	v_mul_lo_u32 v19, v4, s42
	global_load_lds_dwordx4 v192, s[56:57]
	s_mov_b32 m0, s70
	s_add_u32 s26, s24, s50
	v_add_lshl_u32 v190, v2, v19, 1
	global_load_lds_dwordx4 v188, s[24:25]
	s_mov_b32 m0, s71
	s_addc_u32 s27, s25, s51
	s_add_i32 s74, s70, 0x4000
	global_load_lds_dwordx4 v190, s[24:25]
	s_mov_b32 m0, s74
	s_add_i32 s75, s70, 0x6000
	global_load_lds_dwordx4 v188, s[26:27]
	s_mov_b32 m0, s75
	v_mov_b32_e32 v193, v1
	global_load_lds_dwordx4 v190, s[26:27]
	s_load_dwordx2 s[30:31], s[0:1], 0x68
	s_load_dwordx2 s[28:29], s[0:1], 0x78
	s_load_dwordx2 s[26:27], s[0:1], 0x98
	s_cmp_eq_u32 s13, 1
	v_lshl_add_u64 v[4:5], s[56:57], 0, v[0:1]
	v_lshl_add_u64 v[2:3], s[56:57], 0, v[192:193]
	s_cselect_b64 s[56:57], -1, 0
	v_mov_b32_e32 v189, v1
	v_mov_b32_e32 v191, v1
	v_writelane_b32 v254, s56, 43
	s_mov_b32 s2, 0x8000
	v_lshl_add_u64 v[10:11], s[46:47], 0, v[0:1]
	v_lshl_add_u64 v[6:7], s[46:47], 0, v[192:193]
	v_lshl_add_u64 v[8:9], s[24:25], 0, v[188:189]
	v_writelane_b32 v254, s57, 44
	s_cmp_lg_u32 s13, 1
	v_lshl_add_u64 v[12:13], s[24:25], 0, v[190:191]
	s_cbranch_scc1 .LBB0_642
	s_barrier
.LBB0_642:
	s_mul_i32 s56, s62, 0x300
	s_ashr_i32 s57, s56, 31
	s_lshl_b64 s[56:57], s[56:57], 2
	s_waitcnt lgkmcnt(0)
	s_add_u32 s30, s30, s56
	s_addc_u32 s31, s31, s57
	s_add_u32 s28, s28, s56
	v_writelane_b32 v254, s28, 45
	s_addc_u32 s28, s29, s57
	v_writelane_b32 v254, s28, 47
	s_mul_i32 s28, s62, 0x180
	s_ashr_i32 s29, s28, 31
	s_lshl_b64 s[28:29], s[28:29], 2
	s_add_u32 s26, s26, s28
	v_writelane_b32 v254, s62, 38
	s_addc_u32 s27, s27, s29
	v_writelane_b32 v254, s26, 49
	v_bfe_u32 v214, v20, 4, 2
	v_and_b32_e32 v215, 15, v20
	v_writelane_b32 v254, s27, 50
	s_load_dwordx2 s[26:27], s[0:1], 0x120
	v_lshlrev_b32_e32 v21, 4, v214
	v_lshlrev_b32_e32 v20, 2, v20
	v_lshl_or_b32 v21, v215, 6, v21
	v_and_b32_e32 v20, 32, v20
	s_waitcnt lgkmcnt(0)
	s_add_u32 s58, s26, 0x4500000
	s_addc_u32 s59, s27, 0
	s_lshl_b32 s79, s13, 6
	s_lshl_b32 s13, s13, 13
	s_waitcnt vmcnt(0)
	v_bitop3_b32 v22, v21, s13, v20 bitop3:0xde
	s_lshl_b32 s13, s45, 5
	s_and_b32 s80, s13, 0x60
	s_lshl_b32 s13, s80, 7
	s_add_i32 m0, s70, 0x18000
	v_lshl_add_u64 v[10:11], v[10:11], 0, s[6:7]
	v_bitop3_b32 v216, s13, v21, v20 bitop3:0xf6
	s_waitcnt vmcnt(2)
	s_barrier
	global_load_lds_dwordx4 v[10:11], off
	v_lshl_add_u64 v[6:7], v[6:7], 0, s[6:7]
	s_add_i32 m0, s70, 0x1a000
	s_add_i32 s13, s70, 0x8000
	global_load_lds_dwordx4 v[6:7], off
	v_lshl_add_u64 v[6:7], v[8:9], 0, s[6:7]
	s_mov_b32 m0, s13
	s_add_i32 s81, s70, 0xa000
	global_load_lds_dwordx4 v[6:7], off
	v_lshl_add_u64 v[6:7], v[12:13], 0, s[6:7]
	s_mov_b32 m0, s81
	v_lshl_add_u64 v[4:5], v[4:5], 0, s[6:7]
	global_load_lds_dwordx4 v[6:7], off
	s_add_i32 m0, s70, 0x1c000
	v_lshl_add_u64 v[2:3], v[2:3], 0, s[6:7]
	global_load_lds_dwordx4 v[4:5], off
	s_add_i32 m0, s70, 0x1e000
	s_lshr_b32 s26, s43, 26
	global_load_lds_dwordx4 v[2:3], off
	s_add_i32 s26, s42, s26
	s_mov_b32 s78, 2
	s_cmp_gt_i32 s42, 63
	s_cselect_b64 s[60:61], -1, 0
	s_add_i32 s82, s78, -2
	s_cmpk_lt_u32 s44, 0x100
	s_cselect_b64 s[62:63], -1, 0
	s_lshl_b32 s85, s12, 3
	s_abs_i32 s89, s85
	v_cvt_f32_u32_e32 v2, s89
	v_readlane_b32 s26, v254, 29
	s_ashr_i32 s84, s26, 31
	s_bfe_i32 s88, s12, 0x1001c
	v_rcp_iflag_f32_e32 v2, v2
	s_sub_i32 s12, 0, s89
	v_mov_b32_e32 v3, v1
	s_waitcnt vmcnt(6)
	v_mul_f32_e32 v2, 0x4f7ffffe, v2
	v_cvt_u32_f32_e32 v2, v2
	s_ashr_i32 s83, s90, 31
	s_ashr_i32 s49, s48, 31
	s_mov_b32 s92, 0
	v_readfirstlane_b32 s26, v2
	v_add_u32_e32 v2, v16, v14
	v_add_lshl_u32 v2, v2, v15, 1
	s_mul_i32 s12, s12, s26
	v_lshl_add_u64 v[194:195], s[50:51], 0, v[2:3]
	v_add_u32_e32 v2, v19, v17
	s_mul_hi_u32 s12, s26, s12
	v_add_lshl_u32 v2, v2, v18, 1
	s_add_i32 s12, s26, s12
	v_lshl_add_u64 v[196:197], s[50:51], 0, v[2:3]
	v_add_u32_e32 v217, 0, v22
	s_barrier
	s_branch .LBB0_645

.Llmap1_done:
	s_cmp_ge_u32 s93, 6
	s_cselect_b32 s98, 0x100, 0
.LBB0_647:
	s_nop 0
	v_cndmask_b32_e64 v2, 0, 1, s[44:45]
	v_cmp_ne_u32_e64 s[42:43], 1, v2
	s_andn2_b64 vcc, exec, s[44:45]
	s_mov_b64 s[64:65], s[24:25]
	s_cbranch_vccnz .LBB0_649
	s_ashr_i32 s26, s94, 31
	s_mul_hi_u32 s27, s52, s94
	s_mul_i32 s26, s52, s26
	s_add_i32 s26, s27, s26
	s_mul_i32 s27, s53, s94
	s_add_i32 s26, s26, s27
	s_mul_i32 s27, s52, s94
	s_add_u32 s64, s14, s27
	s_addc_u32 s65, s15, s26
	s_add_u32 s64, s64, s98
	s_addc_u32 s65, s65, 0
.LBB0_649:
	s_and_b64 vcc, exec, s[42:43]
	s_mov_b64 s[66:67], s[46:47]
	s_cbranch_vccnz .LBB0_651
	s_ashr_i32 s26, s93, 31
	s_mul_hi_u32 s27, s52, s93
	s_mul_i32 s26, s52, s26
	s_add_i32 s26, s27, s26
	s_mul_i32 s27, s53, s93
	s_add_i32 s26, s26, s27
	s_mul_i32 s27, s52, s93
	s_add_u32 s66, s35, s27
	s_addc_u32 s67, s36, s26
	s_add_u32 s66, s66, s98
	s_addc_u32 s67, s67, 0
